# E10 + per-layer RMSNorm rows software-pipelined: next row prefetched into a second register set, loop-top wait counts only the prefetch
# speedup vs baseline: 1.0081x; 1.0081x over previous
; #define LAS __attribute__((address_space(3)))
; __device__ __forceinline__ unsigned cvt_pk_bf16(float lo, float hi) { f32x2_c v = {lo, hi}; bf16x2_c b = __builtin_convertvector(v, bf16x2_c); return __builtin_bit_cast(unsigned, b); }
; __global__ void __launch_bounds__(NWAVES * 64, 2) mk_fwd(Args args) {
;     ...
;             for (int i = tid; i < 2048; i += 512) { gL[i] = norm_w[l * 2048 + i] * (1.f + MODV[l * 6144 + 2048 + i]); sL[i] = MODV[l * 6144 + i]; }
;             __syncthreads();
;             for (int m = gw; m < SEQ; m += NGW) {
;                 const f32x4* xr = (const f32x4*)(xcur + (size_t)m * DMODEL) + lane;
;                 f32x4 v[8]; float s = 0.f;
; #pragma unroll
;                 for (int j = 0; j < 8; ++j) { v[j] = xr[64 * j]; s += (v[j][0] * v[j][0] + v[j][1] * v[j][1]) + (v[j][2] * v[j][2] + v[j][3] * v[j][3]); }
;                 const float rstd = __builtin_amdgcn_rsqf(wave_sum(s) * (1.f / DMODEL) + EPS);
;                 u32x2* o8 = (u32x2*)(Hb + (size_t)m * DMODEL) + lane;
; #pragma unroll
;                 for (int j = 0; j < 8; ++j) { const f32x4 g = *(const LAS f32x4*)(gL + 4 * lane + 256 * j), sh = *(const LAS f32x4*)(sL + 4 * lane + 256 * j);
;                     const f32x4 y = v[j] * rstd * g + sh; u32x2 w; w.x = cvt_pk_bf16(y[0], y[1]); w.y = cvt_pk_bf16(y[2], y[3]); o8[64 * j] = w; }
;             }
.LBB0_134:
	s_or_b64 exec, exec, s[4:5]
	s_ashr_i32 s1, s1, 6
	s_lshl_b32 s0, s0, 3
	s_add_i32 s4, s0, s1
	s_cmpk_gt_i32 s4, 0x3fff
	s_waitcnt lgkmcnt(0)
	s_barrier
	s_cbranch_scc1 .LBB0_137
	v_and_b32_e32 v66, 63, v0
	v_and_b32_e32 v0, 64, v252
	v_add_u32_e32 v0, 64, v0
	v_xor_b32_e32 v1, 1, v252
	v_cmp_lt_i32_e32 vcc, v1, v0
	v_lshlrev_b32_e32 v188, 4, v66
	v_add_u32_e32 v60, 0, v188
	v_cndmask_b32_e32 v1, v252, v1, vcc
	v_lshlrev_b32_e32 v100, 2, v1
	v_xor_b32_e32 v1, 2, v252
	v_cmp_lt_i32_e32 vcc, v1, v0
	s_add_u32 s0, s20, 0x20e00000
	s_addc_u32 s1, s21, 0
	v_cndmask_b32_e32 v1, v252, v1, vcc
	v_lshlrev_b32_e32 v101, 2, v1
	v_xor_b32_e32 v1, 4, v252
	v_cmp_lt_i32_e32 vcc, v1, v0
	s_cmp_eq_u32 s68, 0
	s_cselect_b32 s9, s9, s1
	v_cndmask_b32_e32 v1, v252, v1, vcc
	v_lshlrev_b32_e32 v102, 2, v1
	v_xor_b32_e32 v1, 8, v252
	v_cmp_lt_i32_e32 vcc, v1, v0
	s_cselect_b32 s8, s8, s0
	s_ashr_i32 s5, s4, 31
	v_cndmask_b32_e32 v1, v252, v1, vcc
	v_lshlrev_b32_e32 v103, 2, v1
	v_xor_b32_e32 v1, 16, v252
	v_cmp_lt_i32_e32 vcc, v1, v0
	s_lshl_b64 s[0:1], s[4:5], 13
	s_add_u32 s0, s8, s0
	v_cndmask_b32_e32 v1, v252, v1, vcc
	v_lshlrev_b32_e32 v104, 2, v1
	v_xor_b32_e32 v1, 32, v252
	v_cmp_lt_i32_e32 vcc, v1, v0
	s_addc_u32 s1, s9, s1
	v_lshl_add_u64 v[64:65], s[0:1], 0, v[188:189]
	v_cndmask_b32_e32 v0, v252, v1, vcc
	v_lshlrev_b32_e32 v105, 2, v0
	ds_read_b128 v[0:3], v60
	ds_read_b128 v[4:7], v60 offset:1024
	ds_read_b128 v[8:11], v60 offset:8192
	ds_read_b128 v[12:15], v60 offset:9216
	ds_read_b128 v[16:19], v60 offset:2048
	ds_read_b128 v[20:23], v60 offset:3072
	ds_read_b128 v[24:27], v60 offset:10240
	ds_read_b128 v[28:31], v60 offset:11264
	ds_read_b128 v[32:35], v60 offset:4096
	ds_read_b128 v[36:39], v60 offset:5120
	ds_read_b128 v[40:43], v60 offset:12288
	ds_read_b128 v[44:47], v60 offset:13312
	ds_read_b128 v[48:51], v60 offset:6144
	ds_read_b128 v[52:55], v60 offset:7168
	ds_read_b128 v[56:59], v60 offset:14336
	ds_read_b128 v[60:63], v60 offset:15360
	s_mov_b64 s[0:1], 0x1000
	v_lshl_add_u64 v[96:97], v[64:65], 0, s[0:1]
	s_lshl_b64 s[0:1], s[4:5], 12
	s_add_u32 s0, s6, s0
	s_addc_u32 s1, s7, s1
	v_readlane_b32 s5, v255, 18
	s_add_u32 s0, s5, s0
	v_readlane_b32 s5, v255, 19
	v_readlane_b32 s10, v255, 20
	v_lshlrev_b32_e32 v188, 3, v66
	s_addc_u32 s1, s5, s1
	v_readlane_b32 s11, v255, 21
	v_lshl_add_u64 v[98:99], s[0:1], 0, v[188:189]
	global_load_dwordx4 v[144:147], v[96:97], off offset:-4096
	global_load_dwordx4 v[140:143], v[96:97], off offset:-3072
	global_load_dwordx4 v[148:151], v[96:97], off offset:-2048
	global_load_dwordx4 v[152:155], v[96:97], off
	global_load_dwordx4 v[156:159], v[96:97], off offset:-1024
	global_load_dwordx4 v[160:163], v[96:97], off offset:1024
	global_load_dwordx4 v[164:167], v[96:97], off offset:3072
	global_load_dwordx4 v[168:171], v[96:97], off offset:2048
	v_lshl_add_u64 v[96:97], v[96:97], 0, s[60:61]
	s_waitcnt vmcnt(0)
.LBB0_136:
	s_add_i32 s4, s4, s58
	s_cmpk_gt_i32 s4, 0x3fff
	s_waitcnt vmcnt(8)
	v_mov_b64_e32 v[64:65], v[140:141]
	v_mov_b64_e32 v[66:67], v[142:143]
	v_mov_b64_e32 v[68:69], v[144:145]
	v_mov_b64_e32 v[70:71], v[146:147]
	v_mov_b64_e32 v[72:73], v[148:149]
	v_mov_b64_e32 v[74:75], v[150:151]
	v_mov_b64_e32 v[76:77], v[152:153]
	v_mov_b64_e32 v[78:79], v[154:155]
	v_mov_b64_e32 v[80:81], v[156:157]
	v_mov_b64_e32 v[82:83], v[158:159]
	v_mov_b64_e32 v[84:85], v[160:161]
	v_mov_b64_e32 v[86:87], v[162:163]
	v_mov_b64_e32 v[88:89], v[164:165]
	v_mov_b64_e32 v[90:91], v[166:167]
	v_mov_b64_e32 v[92:93], v[168:169]
	v_mov_b64_e32 v[94:95], v[170:171]
	s_cbranch_scc1 .Lnorm_nopf
	global_load_dwordx4 v[144:147], v[96:97], off offset:-4096
	global_load_dwordx4 v[140:143], v[96:97], off offset:-3072
	global_load_dwordx4 v[148:151], v[96:97], off offset:-2048
	global_load_dwordx4 v[152:155], v[96:97], off
	global_load_dwordx4 v[156:159], v[96:97], off offset:-1024
	global_load_dwordx4 v[160:163], v[96:97], off offset:1024
	global_load_dwordx4 v[164:167], v[96:97], off offset:3072
	global_load_dwordx4 v[168:171], v[96:97], off offset:2048
	v_lshl_add_u64 v[96:97], v[96:97], 0, s[60:61]
; #define LAS __attribute__((address_space(3)))
; __device__ __forceinline__ unsigned cvt_pk_bf16(float lo, float hi) { f32x2_c v = {lo, hi}; bf16x2_c b = __builtin_convertvector(v, bf16x2_c); return __builtin_bit_cast(unsigned, b); }
; __global__ void __launch_bounds__(NWAVES * 64, 2) mk_fwd(Args args) {
;     ...
;             for (int m = gw; m < SEQ; m += NGW) {
;                 const f32x4* xr = (const f32x4*)(xcur + (size_t)m * DMODEL) + lane;
;                 f32x4 v[8]; float s = 0.f;
; #pragma unroll
;                 for (int j = 0; j < 8; ++j) { v[j] = xr[64 * j]; s += (v[j][0] * v[j][0] + v[j][1] * v[j][1]) + (v[j][2] * v[j][2] + v[j][3] * v[j][3]); }
;                 const float rstd = __builtin_amdgcn_rsqf(wave_sum(s) * (1.f / DMODEL) + EPS);
;                 u32x2* o8 = (u32x2*)(Hb + (size_t)m * DMODEL) + lane;
; #pragma unroll
;                 for (int j = 0; j < 8; ++j) { const f32x4 g = *(const LAS f32x4*)(gL + 4 * lane + 256 * j), sh = *(const LAS f32x4*)(sL + 4 * lane + 256 * j);
;                     const f32x4 y = v[j] * rstd * g + sh; u32x2 w; w.x = cvt_pk_bf16(y[0], y[1]); w.y = cvt_pk_bf16(y[2], y[3]); o8[64 * j] = w; }
;             }
.Lnorm_nopf:
	v_mov_b32_e32 v108, v69
	v_mov_b32_e32 v109, v65
	v_mov_b32_e32 v112, v71
	v_mov_b32_e32 v113, v67
	v_mov_b32_e32 v106, v68
	v_mov_b32_e32 v107, v64
	v_mov_b32_e32 v110, v70
	v_mov_b32_e32 v111, v66
	v_pk_mul_f32 v[114:115], v[74:75], v[74:75]
	v_pk_mul_f32 v[116:117], v[72:73], v[72:73]
	v_pk_mul_f32 v[108:109], v[108:109], v[108:109]
	v_pk_mul_f32 v[112:113], v[112:113], v[112:113]
	v_pk_mov_b32 v[130:131], v[116:117], v[114:115] op_sel:[1,0]
	v_mov_b32_e32 v117, v115
	v_pk_fma_f32 v[106:107], v[106:107], v[106:107], v[108:109]
	v_pk_fma_f32 v[108:109], v[110:111], v[110:111], v[112:113]
	v_mul_f32_e32 v118, v81, v81
	v_mul_f32_e32 v120, v83, v83
	v_pk_add_f32 v[110:111], v[130:131], v[116:117]
	v_pk_add_f32 v[106:107], v[106:107], v[108:109]
	v_mul_f32_e32 v129, v76, v76
	v_mul_f32_e32 v132, v77, v77
	v_mul_f32_e32 v133, v78, v78
	v_mul_f32_e32 v134, v79, v79
	v_pk_fma_f32 v[114:115], v[80:81], v[80:81], v[118:119] op_sel_hi:[1,1,0]
	v_pk_fma_f32 v[118:119], v[82:83], v[82:83], v[120:121] op_sel_hi:[1,1,0]
	v_pk_add_f32 v[108:109], v[110:111], v[110:111] op_sel:[0,1] op_sel_hi:[1,0]
	v_pk_add_f32 v[106:107], v[106:107], v[106:107] op_sel:[0,1] op_sel_hi:[1,0]
	v_pk_mul_f32 v[122:123], v[86:87], v[86:87]
	v_pk_mul_f32 v[124:125], v[84:85], v[84:85]
	v_mov_b32_e32 v115, v133
	v_mov_b32_e32 v119, v134
	v_mov_b32_e32 v109, v132
	v_mov_b32_e32 v107, v129
	v_pk_mov_b32 v[120:121], v[124:125], v[122:123] op_sel:[1,0]
	v_mov_b32_e32 v125, v123
	v_pk_add_f32 v[110:111], v[114:115], v[118:119]
	v_pk_add_f32 v[106:107], v[106:107], v[108:109]
	v_mul_f32_e32 v126, v93, v93
	v_mul_f32_e32 v128, v95, v95
	v_pk_add_f32 v[112:113], v[120:121], v[124:125]
	v_pk_add_f32 v[106:107], v[106:107], v[110:111]
	v_mul_f32_e32 v135, v88, v88
	v_mul_f32_e32 v136, v89, v89
	v_mul_f32_e32 v137, v90, v90
	v_mul_f32_e32 v138, v91, v91
	v_pk_fma_f32 v[122:123], v[92:93], v[92:93], v[126:127] op_sel_hi:[1,1,0]
	v_pk_fma_f32 v[126:127], v[94:95], v[94:95], v[128:129] op_sel_hi:[1,1,0]
	v_pk_add_f32 v[112:113], v[112:113], v[112:113] op_sel:[0,1] op_sel_hi:[1,0]
	v_pk_add_f32 v[106:107], v[106:107], v[106:107] op_sel:[0,1] op_sel_hi:[1,0]
	v_mov_b32_e32 v123, v137
	v_mov_b32_e32 v127, v138
	v_mov_b32_e32 v113, v136
	v_mov_b32_e32 v107, v135
	v_pk_add_f32 v[114:115], v[122:123], v[126:127]
	v_pk_add_f32 v[106:107], v[106:107], v[112:113]
	s_nop 0
	v_pk_add_f32 v[106:107], v[106:107], v[114:115]
	s_nop 0
	v_add_f32_e32 v106, v106, v107
	ds_bpermute_b32 v107, v100, v106
	s_waitcnt lgkmcnt(0)
	v_add_f32_e32 v106, v106, v107
	ds_bpermute_b32 v107, v101, v106
	s_waitcnt lgkmcnt(0)
	v_add_f32_e32 v106, v106, v107
	ds_bpermute_b32 v107, v102, v106
	s_waitcnt lgkmcnt(0)
	v_add_f32_e32 v106, v106, v107
	ds_bpermute_b32 v107, v103, v106
	s_waitcnt lgkmcnt(0)
	v_add_f32_e32 v106, v106, v107
	ds_bpermute_b32 v107, v104, v106
	s_waitcnt lgkmcnt(0)
	v_add_f32_e32 v106, v106, v107
	ds_bpermute_b32 v107, v105, v106
	s_waitcnt lgkmcnt(0)
	v_add_f32_e32 v106, v106, v107
	v_fmamk_f32 v106, v106, 0x3a000000, v253
	v_rsq_f32_e32 v106, v106
	s_nop 0
	v_pk_mul_f32 v[68:69], v[106:107], v[68:69] op_sel_hi:[0,1]
	v_pk_mul_f32 v[70:71], v[106:107], v[70:71] op_sel_hi:[0,1]
	v_pk_mul_f32 v[64:65], v[106:107], v[64:65] op_sel_hi:[0,1]
	v_pk_mul_f32 v[66:67], v[106:107], v[66:67] op_sel_hi:[0,1]
	v_pk_mul_f32 v[72:73], v[106:107], v[72:73] op_sel_hi:[0,1]
	v_pk_mul_f32 v[74:75], v[106:107], v[74:75] op_sel_hi:[0,1]
	v_pk_mul_f32 v[80:81], v[106:107], v[80:81] op_sel_hi:[0,1]
	v_pk_mul_f32 v[82:83], v[106:107], v[82:83] op_sel_hi:[0,1]
	v_pk_mul_f32 v[76:77], v[106:107], v[76:77] op_sel_hi:[0,1]
	v_pk_mul_f32 v[78:79], v[106:107], v[78:79] op_sel_hi:[0,1]
	v_pk_mul_f32 v[84:85], v[106:107], v[84:85] op_sel_hi:[0,1]
	v_pk_mul_f32 v[86:87], v[106:107], v[86:87] op_sel_hi:[0,1]
	v_pk_mul_f32 v[92:93], v[106:107], v[92:93] op_sel_hi:[0,1]
	v_pk_mul_f32 v[94:95], v[106:107], v[94:95] op_sel_hi:[0,1]
	v_pk_mul_f32 v[88:89], v[106:107], v[88:89] op_sel_hi:[0,1]
	v_pk_mul_f32 v[90:91], v[106:107], v[90:91] op_sel_hi:[0,1]
	v_pk_fma_f32 v[70:71], v[2:3], v[70:71], v[10:11]
	v_pk_fma_f32 v[68:69], v[0:1], v[68:69], v[8:9]
	v_pk_fma_f32 v[66:67], v[6:7], v[66:67], v[14:15]
	v_pk_fma_f32 v[64:65], v[4:5], v[64:65], v[12:13]
	v_pk_fma_f32 v[74:75], v[18:19], v[74:75], v[26:27]
	v_pk_fma_f32 v[72:73], v[16:17], v[72:73], v[24:25]
	v_pk_fma_f32 v[82:83], v[22:23], v[82:83], v[30:31]
	v_pk_fma_f32 v[80:81], v[20:21], v[80:81], v[28:29]
	v_pk_fma_f32 v[78:79], v[34:35], v[78:79], v[42:43]
	v_pk_fma_f32 v[76:77], v[32:33], v[76:77], v[40:41]
	v_pk_fma_f32 v[86:87], v[38:39], v[86:87], v[46:47]
	v_pk_fma_f32 v[84:85], v[36:37], v[84:85], v[44:45]
	v_pk_fma_f32 v[94:95], v[50:51], v[94:95], v[58:59]
	v_pk_fma_f32 v[92:93], v[48:49], v[92:93], v[56:57]
	v_pk_fma_f32 v[90:91], v[54:55], v[90:91], v[62:63]
	v_pk_fma_f32 v[88:89], v[52:53], v[88:89], v[60:61]
	v_cvt_pk_bf16_f32 v68, v68, v69
	v_cvt_pk_bf16_f32 v69, v70, v71
	v_cvt_pk_bf16_f32 v64, v64, v65
	v_cvt_pk_bf16_f32 v65, v66, v67
	v_cvt_pk_bf16_f32 v66, v72, v73
	v_cvt_pk_bf16_f32 v67, v74, v75
	v_cvt_pk_bf16_f32 v70, v80, v81
	v_cvt_pk_bf16_f32 v71, v82, v83
	v_cvt_pk_bf16_f32 v72, v76, v77
	v_cvt_pk_bf16_f32 v73, v78, v79
	v_cvt_pk_bf16_f32 v74, v84, v85
	v_cvt_pk_bf16_f32 v75, v86, v87
	v_cvt_pk_bf16_f32 v76, v92, v93
	v_cvt_pk_bf16_f32 v77, v94, v95
	v_cvt_pk_bf16_f32 v78, v88, v89
	v_cvt_pk_bf16_f32 v79, v90, v91
	global_store_dwordx2 v[98:99], v[68:69], off offset:-2048
	global_store_dwordx2 v[98:99], v[64:65], off offset:-1536
	global_store_dwordx2 v[98:99], v[66:67], off offset:-1024
	global_store_dwordx2 v[98:99], v[70:71], off offset:-512
	global_store_dwordx2 v[98:99], v[72:73], off
	global_store_dwordx2 v[98:99], v[74:75], off offset:512
	global_store_dwordx2 v[98:99], v[76:77], off offset:1024
	global_store_dwordx2 v[98:99], v[78:79], off offset:1536
	v_lshl_add_u64 v[98:99], v[98:99], 0, s[10:11]
	s_cbranch_scc0 .LBB0_136
